# code warming at barriers extended to 24 KB of the next phase's code
# speedup vs baseline: 1.0003x; 1.0003x over previous
; __device__ __forceinline__ unsigned xb_ld(unsigned* p)              { return __hip_atomic_load(p, __ATOMIC_RELAXED, __HIP_MEMORY_SCOPE_AGENT); }
; __device__ __forceinline__ unsigned xb_add(unsigned* p, unsigned v) { return __hip_atomic_fetch_add(p, v, __ATOMIC_RELAXED, __HIP_MEMORY_SCOPE_AGENT); }
; #define XB_SPIN(cond, bar) do { unsigned _sp = 0; while (cond) { __builtin_amdgcn_s_sleep(1); \
;     if ((++_sp & 255u) == 0u) { if (xb_ld(&(bar)[XB_TMO])) break; if (_sp > XB_SPIN_CAP) { atomicAdd(&(bar)[XB_TMO], 1u); break; } } } } while (0)
; __device__ __forceinline__ void xcd_barrier(const XcdBarrier& b) {
;     asm volatile("s_waitcnt vmcnt(0)" ::: "memory");
;     __syncthreads();
;     if (threadIdx.x == 0) {
;         unsigned* bar = b.bar;
;         __builtin_amdgcn_s_waitcnt(0);
;         unsigned nloc = b.st[0], nx = b.st[1];
;         if (nloc == 0u) { xcd_barrier_complete(bar, b.x, nloc, nx); b.st[0] = nloc; b.st[1] = nx; }
;         const unsigned old = xb_add(&bar[XB_XSUB(b.x)], 1u);
;         const unsigned gen = old / nloc;
;         if (old + 1u == (gen + 1u) * nloc) {
;             __builtin_amdgcn_fence(__ATOMIC_RELEASE, "agent");
;             asm volatile("s_waitcnt vmcnt(0)" ::: "memory");
;             const unsigned og = xb_add(&bar[XB_TOP], 1u);
;             const unsigned tg = og / nx;
;             if (og + 1u == (tg + 1u) * nx) xb_add(&bar[XB_TOPGEN], 1u);
;             else XB_SPIN(xb_ld(&bar[XB_TOPGEN]) == tg, bar);
;             __builtin_amdgcn_fence(__ATOMIC_ACQUIRE, "agent");
;             xb_add(&bar[XB_XGEN(b.x)], 1u);
;             asm volatile("s_waitcnt vmcnt(0)" ::: "memory");
;         } else {
;             XB_SPIN(xb_ld(&bar[XB_XGEN(b.x)]) == gen, bar);
;             __builtin_amdgcn_fence(__ATOMIC_ACQUIRE, "agent");
;             asm volatile("s_waitcnt vmcnt(0)" ::: "memory");
;         }
;     }
;     __syncthreads();
.Lwarm_loop_0:
	s_mov_b32 m0, s8
	s_nop 0
	global_load_lds_dwordx4 v[0:1], off
	v_lshl_add_u64 v[0:1], v[0:1], 0, s[2:3]
	s_add_u32 s8, s8, 0x400
	s_cmp_lt_u32 s8, 0x6000
	s_cbranch_scc1 .Lwarm_loop_0
	s_waitcnt vmcnt(0)
